# row passes (st2/7/10): first four butterfly hops of each wave sum via DPP moves (quad_perm / row_half_mirror / row_mirror) instead of ds_bpermute round trips
# baseline (speedup 1.0000x reference)
.LBB0_562:
	s_lshl_b32 s6, s24, 3
	s_ashr_i32 s7, s6, 31
	v_lshlrev_b32_e32 v49, 2, v116
	s_lshl_b64 s[10:11], s[6:7], 10
	v_mov_b32_e32 v217, s11
	v_or_b32_e32 v216, s10, v49
	v_lshlrev_b64 v[66:67], 1, v[216:217]
	v_lshl_add_u64 v[218:219], s[8:9], 0, v[66:67]
	v_lshl_add_u64 v[66:67], s[38:39], 0, v[66:67]
	global_load_dwordx2 v[90:91], v[218:219], off
	global_load_dwordx2 v[224:225], v[218:219], off offset:512
	global_load_dwordx2 v[222:223], v[218:219], off offset:1024
	global_load_dwordx2 v[220:221], v[218:219], off offset:1536
	global_load_dwordx2 v[86:87], v[66:67], off
	global_load_dwordx2 v[88:89], v[66:67], off offset:512
	global_load_dwordx2 v[92:93], v[66:67], off offset:1024
	global_load_dwordx2 v[230:231], v[66:67], off offset:1536
	s_or_b32 s10, s6, 1
	s_ashr_i32 s11, s10, 31
	s_lshl_b64 s[10:11], s[10:11], 10
	v_or_b32_e32 v196, s10, v49
	s_or_b32 s10, s6, 2
	v_mov_b32_e32 v197, s11
	s_ashr_i32 s11, s10, 31
	s_lshl_b64 s[10:11], s[10:11], 10
	v_or_b32_e32 v176, s10, v49
	s_or_b32 s10, s6, 3
	v_mov_b32_e32 v177, s11
	s_ashr_i32 s11, s10, 31
	s_lshl_b64 s[10:11], s[10:11], 10
	v_lshlrev_b64 v[66:67], 1, v[196:197]
	v_or_b32_e32 v156, s10, v49
	s_or_b32 s10, s6, 4
	v_lshl_add_u64 v[198:199], s[8:9], 0, v[66:67]
	v_lshl_add_u64 v[66:67], s[38:39], 0, v[66:67]
	v_mov_b32_e32 v157, s11
	s_ashr_i32 s11, s10, 31
	global_load_dwordx2 v[206:207], v[198:199], off
	global_load_dwordx2 v[204:205], v[198:199], off offset:512
	global_load_dwordx2 v[202:203], v[198:199], off offset:1024
	global_load_dwordx2 v[200:201], v[198:199], off offset:1536
	global_load_dwordx2 v[214:215], v[66:67], off
	global_load_dwordx2 v[212:213], v[66:67], off offset:512
	global_load_dwordx2 v[210:211], v[66:67], off offset:1024
	global_load_dwordx2 v[208:209], v[66:67], off offset:1536
	v_lshlrev_b64 v[66:67], 1, v[176:177]
	s_lshl_b64 s[10:11], s[10:11], 10
	v_lshl_add_u64 v[178:179], s[8:9], 0, v[66:67]
	v_lshl_add_u64 v[66:67], s[38:39], 0, v[66:67]
	v_or_b32_e32 v134, s10, v49
	s_or_b32 s10, s6, 5
	global_load_dwordx2 v[186:187], v[178:179], off
	global_load_dwordx2 v[184:185], v[178:179], off offset:512
	global_load_dwordx2 v[182:183], v[178:179], off offset:1024
	global_load_dwordx2 v[180:181], v[178:179], off offset:1536
	global_load_dwordx2 v[194:195], v[66:67], off
	global_load_dwordx2 v[192:193], v[66:67], off offset:512
	global_load_dwordx2 v[190:191], v[66:67], off offset:1024
	global_load_dwordx2 v[188:189], v[66:67], off offset:1536
	v_lshlrev_b64 v[66:67], 1, v[156:157]
	v_mov_b32_e32 v135, s11
	s_ashr_i32 s11, s10, 31
	v_lshl_add_u64 v[158:159], s[8:9], 0, v[66:67]
	v_lshl_add_u64 v[66:67], s[38:39], 0, v[66:67]
	s_lshl_b64 s[10:11], s[10:11], 10
	global_load_dwordx2 v[166:167], v[158:159], off
	global_load_dwordx2 v[164:165], v[158:159], off offset:512
	global_load_dwordx2 v[162:163], v[158:159], off offset:1024
	global_load_dwordx2 v[160:161], v[158:159], off offset:1536
	global_load_dwordx2 v[174:175], v[66:67], off
	global_load_dwordx2 v[172:173], v[66:67], off offset:512
	global_load_dwordx2 v[170:171], v[66:67], off offset:1024
	global_load_dwordx2 v[168:169], v[66:67], off offset:1536
	v_lshlrev_b64 v[66:67], 1, v[134:135]
	v_or_b32_e32 v114, s10, v49
	s_or_b32 s10, s6, 6
	v_lshl_add_u64 v[136:137], s[8:9], 0, v[66:67]
	v_lshl_add_u64 v[66:67], s[38:39], 0, v[66:67]
	v_mov_b32_e32 v115, s11
	s_ashr_i32 s11, s10, 31
	global_load_dwordx2 v[146:147], v[136:137], off
	global_load_dwordx2 v[142:143], v[136:137], off offset:512
	global_load_dwordx2 v[140:141], v[136:137], off offset:1024
	global_load_dwordx2 v[138:139], v[136:137], off offset:1536
	global_load_dwordx2 v[154:155], v[66:67], off
	global_load_dwordx2 v[152:153], v[66:67], off offset:512
	global_load_dwordx2 v[150:151], v[66:67], off offset:1024
	global_load_dwordx2 v[148:149], v[66:67], off offset:1536
	v_lshlrev_b64 v[66:67], 1, v[114:115]
	s_lshl_b64 s[10:11], s[10:11], 10
	v_lshl_add_u64 v[116:117], s[8:9], 0, v[66:67]
	v_lshl_add_u64 v[66:67], s[38:39], 0, v[66:67]
	v_mov_b32_e32 v95, s11
	v_or_b32_e32 v94, s10, v49
	s_or_b32 s6, s6, 7
	global_load_dwordx2 v[124:125], v[116:117], off
	global_load_dwordx2 v[122:123], v[116:117], off offset:512
	global_load_dwordx2 v[120:121], v[116:117], off offset:1024
	global_load_dwordx2 v[118:119], v[116:117], off offset:1536
	global_load_dwordx2 v[132:133], v[66:67], off
	global_load_dwordx2 v[130:131], v[66:67], off offset:512
	global_load_dwordx2 v[128:129], v[66:67], off offset:1024
	global_load_dwordx2 v[126:127], v[66:67], off offset:1536
	v_lshlrev_b64 v[66:67], 1, v[94:95]
	s_ashr_i32 s7, s6, 31
	v_lshl_add_u64 v[96:97], s[8:9], 0, v[66:67]
	v_lshl_add_u64 v[66:67], s[38:39], 0, v[66:67]
	s_lshl_b64 s[6:7], s[6:7], 10
	global_load_dwordx2 v[104:105], v[96:97], off
	global_load_dwordx2 v[102:103], v[96:97], off offset:512
	global_load_dwordx2 v[100:101], v[96:97], off offset:1024
	global_load_dwordx2 v[98:99], v[96:97], off offset:1536
	global_load_dwordx2 v[112:113], v[66:67], off
	global_load_dwordx2 v[110:111], v[66:67], off offset:512
	global_load_dwordx2 v[108:109], v[66:67], off offset:1024
	global_load_dwordx2 v[106:107], v[66:67], off offset:1536
	v_mov_b32_e32 v67, s7
	v_or_b32_e32 v66, s6, v49
	v_lshlrev_b64 v[70:71], 1, v[66:67]
	v_lshl_add_u64 v[68:69], s[8:9], 0, v[70:71]
	v_lshl_add_u64 v[78:79], s[38:39], 0, v[70:71]
	global_load_dwordx2 v[76:77], v[68:69], off
	global_load_dwordx2 v[74:75], v[68:69], off offset:512
	global_load_dwordx2 v[72:73], v[68:69], off offset:1024
	global_load_dwordx2 v[70:71], v[68:69], off offset:1536
	global_load_dwordx2 v[84:85], v[78:79], off
	global_load_dwordx2 v[82:83], v[78:79], off offset:512
	global_load_dwordx2 v[80:81], v[78:79], off offset:1024
	s_nop 0
	global_load_dwordx2 v[78:79], v[78:79], off offset:1536
	v_xor_b32_e32 v144, 4, v49
	v_xor_b32_e32 v251, 32, v49
	v_xor_b32_e32 v252, 64, v49
	s_waitcnt vmcnt(0)
	v_pk_add_f32 v[20:21], v[20:21], 1.0 op_sel_hi:[1,0]
	v_pk_add_f32 v[22:23], v[22:23], 1.0 op_sel_hi:[1,0]
	v_pk_mul_f32 v[20:21], v[48:49], v[20:21] op_sel_hi:[0,1]
	v_pk_mul_f32 v[22:23], v[48:49], v[22:23] op_sel_hi:[0,1]
	s_cmp_lg_u64 s[0:1], 0
	s_cselect_b64 s[8:9], -1, 0
	s_cmp_eq_u64 s[0:1], 0
	v_and_b32_e32 v237, 0xffff0000, v86
	v_and_b32_e32 v249, 0xffff0000, v87
	v_lshlrev_b32_e32 v236, 16, v86
	v_lshlrev_b32_e32 v248, 16, v87
	v_mul_f32_e32 v86, v249, v249
	v_and_b32_e32 v243, 0xffff0000, v89
	v_and_b32_e32 v242, 0xffff0000, v88
	v_lshlrev_b32_e32 v232, 16, v92
	v_and_b32_e32 v233, 0xffff0000, v92
	v_mul_f32_e32 v92, v237, v237
	v_pk_fma_f32 v[86:87], v[248:249], v[248:249], v[86:87] op_sel_hi:[1,1,0]
	v_lshlrev_b32_e32 v241, 16, v89
	v_lshlrev_b32_e32 v240, 16, v88
	v_pk_mul_f32 v[88:89], v[242:243], v[242:243]
	v_lshlrev_b32_e32 v234, 16, v93
	v_and_b32_e32 v235, 0xffff0000, v93
	v_lshlrev_b32_e32 v229, 16, v230
	v_pk_fma_f32 v[92:93], v[236:237], v[236:237], v[92:93] op_sel_hi:[1,1,0]
	v_pk_fma_f32 v[88:89], v[240:241], v[240:241], v[88:89]
	v_and_b32_e32 v227, 0xffff0000, v230
	v_mov_b32_e32 v228, v92
	v_mov_b32_e32 v238, v86
	v_mov_b32_e32 v239, v229
	v_mul_f32_e32 v226, v227, v227
	v_pk_add_f32 v[86:87], v[92:93], v[86:87]
	v_pk_mul_f32 v[92:93], v[228:229], v[238:239]
	v_pk_add_f32 v[88:89], v[88:89], v[88:89] op_sel:[0,1] op_sel_hi:[1,0]
	v_mov_b32_e32 v87, v93
	v_mov_b32_e32 v89, v226
	v_lshlrev_b32_e32 v230, 16, v231
	v_and_b32_e32 v231, 0xffff0000, v231
	v_pk_add_f32 v[86:87], v[86:87], v[88:89]
	v_mul_f32_e32 v88, v233, v233
	v_mul_f32_e32 v92, v235, v235
	v_mul_f32_e32 v246, v230, v230
	v_mul_f32_e32 v250, v231, v231
	v_pk_fma_f32 v[88:89], v[232:233], v[232:233], v[88:89] op_sel_hi:[1,1,0]
	v_pk_fma_f32 v[92:93], v[234:235], v[234:235], v[92:93] op_sel_hi:[1,1,0]
	v_mov_b32_e32 v89, v246
	v_mov_b32_e32 v93, v250
	v_pk_add_f32 v[88:89], v[88:89], v[92:93]
	v_xor_b32_e32 v228, 8, v49
	v_pk_add_f32 v[86:87], v[86:87], v[88:89]
	v_xor_b32_e32 v250, 16, v49
	v_add_f32_e32 v86, v86, v87
	s_nop 1
	v_mov_b32_dpp v87, v86 quad_perm:[1,0,3,2] row_mask:0xf bank_mask:0xf
	v_xor_b32_e32 v246, 0x80, v49
	v_pk_mul_f32 v[88:89], v[18:19], v[22:23]
	v_and_b32_e32 v19, 0xffff0000, v91
	s_waitcnt lgkmcnt(0)
	v_add_f32_e32 v86, v86, v87
	s_nop 1
	v_mov_b32_dpp v87, v86 quad_perm:[2,3,0,1] row_mask:0xf bank_mask:0xf
	s_waitcnt lgkmcnt(0)
	v_add_f32_e32 v86, v86, v87
	s_nop 1
	v_mov_b32_dpp v87, v86 row_half_mirror row_mask:0xf bank_mask:0xf
	s_waitcnt lgkmcnt(0)
	v_add_f32_e32 v86, v86, v87
	s_nop 1
	v_mov_b32_dpp v87, v86 row_mirror row_mask:0xf bank_mask:0xf
	s_waitcnt lgkmcnt(0)
	v_add_f32_e32 v92, v86, v87
	ds_bpermute_b32 v93, v252, v92
	v_pk_mul_f32 v[86:87], v[16:17], v[20:21]
	v_lshlrev_b32_e32 v16, 16, v90
	s_waitcnt lgkmcnt(0)
	v_add_f32_e32 v17, v92, v93
	ds_bpermute_b32 v18, v246, v17
	s_waitcnt lgkmcnt(0)
	v_add_f32_e32 v17, v17, v18
	v_fmamk_f32 v17, v17, 0x3a800000, v247
	v_mul_f32_e32 v18, 0x4b800000, v17
	v_cmp_gt_f32_e32 vcc, s35, v17
	s_nop 1
	v_cndmask_b32_e32 v17, v17, v18, vcc
	v_rsq_f32_e32 v20, v17
	v_and_b32_e32 v17, 0xffff0000, v90
	v_lshlrev_b32_e32 v18, 16, v91
	v_mul_f32_e32 v21, 0x45800000, v20
	v_cndmask_b32_e32 v238, v20, v21, vcc
	v_pk_mul_f32 v[20:21], v[238:239], v[236:237] op_sel_hi:[0,1]
	v_pk_mul_f32 v[22:23], v[238:239], v[248:249] op_sel_hi:[0,1]
	v_pk_fma_f32 v[18:19], v[88:89], v[22:23], v[18:19]
	v_pk_fma_f32 v[16:17], v[86:87], v[20:21], v[16:17]
	v_lshl_add_u64 v[236:237], v[216:217], 2, s[0:1]
	s_cbranch_scc1 .LBB0_573
	global_store_dwordx4 v[236:237], v[16:19], off
	s_cbranch_execnz .LBB0_565

.LBB0_579:
	s_and_b64 vcc, exec, s[4:5]
	s_cbranch_vccnz .LBB0_581
	v_mul_f32_e32 v40, v17, v17
	v_mul_f32_e32 v41, v19, v19
	v_fmac_f32_e32 v40, v16, v16
	v_fmac_f32_e32 v41, v18, v18
	v_add_f32_e32 v40, v40, v41
	v_mul_f32_e32 v41, v21, v21
	v_mul_f32_e32 v42, v23, v23
	v_fmac_f32_e32 v41, v20, v20
	v_fmac_f32_e32 v42, v22, v22
	v_add_f32_e32 v41, v41, v42
	v_add_f32_e32 v40, v40, v41
	v_mul_f32_e32 v41, v25, v25
	v_mul_f32_e32 v42, v27, v27
	v_fmac_f32_e32 v41, v24, v24
	v_fmac_f32_e32 v42, v26, v26
	v_add_f32_e32 v41, v41, v42
	v_add_f32_e32 v40, v41, v40
	v_mul_f32_e32 v41, v29, v29
	v_mul_f32_e32 v42, v31, v31
	v_fmac_f32_e32 v41, v28, v28
	v_fmac_f32_e32 v42, v30, v30
	v_add_f32_e32 v41, v41, v42
	v_add_f32_e32 v40, v41, v40
	s_nop 1
	v_mov_b32_dpp v41, v40 quad_perm:[1,0,3,2] row_mask:0xf bank_mask:0xf
	s_waitcnt lgkmcnt(0)
	v_add_f32_e32 v40, v40, v41
	s_nop 1
	v_mov_b32_dpp v41, v40 quad_perm:[2,3,0,1] row_mask:0xf bank_mask:0xf
	s_waitcnt lgkmcnt(0)
	v_add_f32_e32 v40, v40, v41
	s_nop 1
	v_mov_b32_dpp v41, v40 row_half_mirror row_mask:0xf bank_mask:0xf
	s_waitcnt lgkmcnt(0)
	v_add_f32_e32 v40, v40, v41
	s_nop 1
	v_mov_b32_dpp v41, v40 row_mirror row_mask:0xf bank_mask:0xf
	s_waitcnt lgkmcnt(0)
	v_add_f32_e32 v40, v40, v41
	ds_bpermute_b32 v41, v252, v40
	s_waitcnt lgkmcnt(0)
	v_add_f32_e32 v40, v40, v41
	ds_bpermute_b32 v41, v246, v40
	s_waitcnt lgkmcnt(0)
	v_add_f32_e32 v40, v40, v41
	v_fmamk_f32 v40, v40, 0x3a800000, v247
	v_mul_f32_e32 v41, 0x4b800000, v40
	v_cmp_gt_f32_e32 vcc, s35, v40
	s_nop 1
	v_cndmask_b32_e32 v40, v40, v41, vcc
	v_rsq_f32_e32 v42, v40
	v_lshl_add_u64 v[40:41], v[216:217], 1, s[42:43]
	v_mul_f32_e32 v43, 0x45800000, v42
	v_cndmask_b32_e32 v42, v42, v43, vcc
	v_pk_mul_f32 v[16:17], v[16:17], v[42:43] op_sel_hi:[1,0]
	v_pk_mul_f32 v[18:19], v[18:19], v[42:43] op_sel_hi:[1,0]
	v_pk_mul_f32 v[20:21], v[20:21], v[42:43] op_sel_hi:[1,0]
	v_pk_mul_f32 v[22:23], v[22:23], v[42:43] op_sel_hi:[1,0]
	v_pk_fma_f32 v[18:19], v[54:55], v[18:19], v[2:3]
	v_pk_fma_f32 v[16:17], v[52:53], v[16:17], v[0:1]
	v_pk_fma_f32 v[22:23], v[56:57], v[22:23], v[6:7]
	v_pk_fma_f32 v[20:21], v[50:51], v[20:21], v[4:5]
	v_cvt_pk_bf16_f32 v16, v16, v17
	v_cvt_pk_bf16_f32 v17, v18, v19
	v_cvt_pk_bf16_f32 v18, v20, v21
	v_cvt_pk_bf16_f32 v19, v22, v23
	global_store_dwordx2 v[40:41], v[16:17], off
	global_store_dwordx2 v[40:41], v[18:19], off offset:512
	v_pk_mul_f32 v[16:17], v[24:25], v[42:43] op_sel_hi:[1,0]
	v_pk_mul_f32 v[18:19], v[26:27], v[42:43] op_sel_hi:[1,0]
	v_pk_fma_f32 v[16:17], v[60:61], v[16:17], v[8:9]
	v_pk_fma_f32 v[18:19], v[62:63], v[18:19], v[10:11]
	v_cvt_pk_bf16_f32 v16, v16, v17
	v_cvt_pk_bf16_f32 v17, v18, v19
	global_store_dwordx2 v[40:41], v[16:17], off offset:1024
	v_pk_mul_f32 v[16:17], v[28:29], v[42:43] op_sel_hi:[1,0]
	v_pk_mul_f32 v[18:19], v[30:31], v[42:43] op_sel_hi:[1,0]
	v_pk_fma_f32 v[16:17], v[58:59], v[16:17], v[12:13]
	v_pk_fma_f32 v[18:19], v[64:65], v[18:19], v[14:15]
	v_cvt_pk_bf16_f32 v16, v16, v17
	v_cvt_pk_bf16_f32 v17, v18, v19
	global_store_dwordx2 v[40:41], v[16:17], off offset:1536
.LBB0_581:
	v_and_b32_e32 v17, 0xffff0000, v214
	v_and_b32_e32 v19, 0xffff0000, v215
	v_lshlrev_b32_e32 v16, 16, v214
	v_lshlrev_b32_e32 v18, 16, v215
	v_mul_f32_e32 v20, v19, v19
	v_and_b32_e32 v23, 0xffff0000, v213
	v_and_b32_e32 v22, 0xffff0000, v212
	v_and_b32_e32 v29, 0xffff0000, v208
	v_mul_f32_e32 v28, v17, v17
	v_pk_fma_f32 v[42:43], v[18:19], v[18:19], v[20:21] op_sel_hi:[1,1,0]
	v_lshlrev_b32_e32 v21, 16, v213
	v_lshlrev_b32_e32 v20, 16, v212
	v_pk_mul_f32 v[24:25], v[22:23], v[22:23]
	v_lshlrev_b32_e32 v31, 16, v208
	v_pk_fma_f32 v[46:47], v[16:17], v[16:17], v[28:29] op_sel_hi:[1,1,0]
	v_pk_fma_f32 v[44:45], v[20:21], v[20:21], v[24:25]
	v_mov_b32_e32 v30, v46
	v_mov_b32_e32 v48, v42
	v_mov_b32_e32 v49, v31
	v_and_b32_e32 v25, 0xffff0000, v210
	v_mul_f32_e32 v208, v29, v29
	v_pk_add_f32 v[42:43], v[46:47], v[42:43]
	v_pk_mul_f32 v[46:47], v[30:31], v[48:49]
	v_pk_add_f32 v[44:45], v[44:45], v[44:45] op_sel:[0,1] op_sel_hi:[1,0]
	v_lshlrev_b32_e32 v24, 16, v210
	v_and_b32_e32 v27, 0xffff0000, v211
	v_mov_b32_e32 v43, v47
	v_mov_b32_e32 v45, v208
	v_mul_f32_e32 v28, v25, v25
	v_lshlrev_b32_e32 v26, 16, v211
	v_lshlrev_b32_e32 v40, 16, v209
	v_and_b32_e32 v41, 0xffff0000, v209
	v_pk_add_f32 v[42:43], v[42:43], v[44:45]
	v_pk_fma_f32 v[44:45], v[24:25], v[24:25], v[28:29] op_sel_hi:[1,1,0]
	v_mul_f32_e32 v28, v27, v27
	v_mul_f32_e32 v209, v40, v40
	v_mul_f32_e32 v210, v41, v41
	v_pk_fma_f32 v[46:47], v[26:27], v[26:27], v[28:29] op_sel_hi:[1,1,0]
	v_mov_b32_e32 v45, v209
	v_mov_b32_e32 v47, v210
	v_pk_add_f32 v[44:45], v[44:45], v[46:47]
	v_lshlrev_b32_e32 v46, 16, v207
	v_pk_add_f32 v[42:43], v[42:43], v[44:45]
	v_lshlrev_b32_e32 v44, 16, v206
	v_add_f32_e32 v28, v42, v43
	s_nop 1
	v_mov_b32_dpp v30, v28 quad_perm:[1,0,3,2] row_mask:0xf bank_mask:0xf
	v_and_b32_e32 v45, 0xffff0000, v206
	v_and_b32_e32 v47, 0xffff0000, v207
	s_waitcnt lgkmcnt(0)
	v_add_f32_e32 v28, v28, v30
	s_nop 1
	v_mov_b32_dpp v30, v28 quad_perm:[2,3,0,1] row_mask:0xf bank_mask:0xf
	s_waitcnt lgkmcnt(0)
	v_add_f32_e32 v28, v28, v30
	s_nop 1
	v_mov_b32_dpp v30, v28 row_half_mirror row_mask:0xf bank_mask:0xf
	s_waitcnt lgkmcnt(0)
	v_add_f32_e32 v28, v28, v30
	s_nop 1
	v_mov_b32_dpp v30, v28 row_mirror row_mask:0xf bank_mask:0xf
	s_waitcnt lgkmcnt(0)
	v_add_f32_e32 v28, v28, v30
	ds_bpermute_b32 v30, v252, v28
	s_waitcnt lgkmcnt(0)
	v_add_f32_e32 v28, v28, v30
	ds_bpermute_b32 v30, v246, v28
	s_waitcnt lgkmcnt(0)
	v_add_f32_e32 v28, v28, v30
	v_fmamk_f32 v28, v28, 0x3a800000, v247
	v_mul_f32_e32 v30, 0x4b800000, v28
	v_cmp_gt_f32_e32 vcc, s35, v28
	s_nop 1
	v_cndmask_b32_e32 v28, v28, v30, vcc
	v_rsq_f32_e32 v28, v28
	s_nop 0
	v_mul_f32_e32 v30, 0x45800000, v28
	v_cndmask_b32_e32 v42, v28, v30, vcc
	v_pk_mul_f32 v[16:17], v[42:43], v[16:17] op_sel_hi:[0,1]
	v_pk_mul_f32 v[18:19], v[42:43], v[18:19] op_sel_hi:[0,1]
	v_pk_fma_f32 v[18:19], v[88:89], v[18:19], v[46:47]
	v_pk_fma_f32 v[16:17], v[86:87], v[16:17], v[44:45]
	s_and_b64 vcc, exec, s[6:7]
	v_lshl_add_u64 v[44:45], v[196:197], 2, s[0:1]
	s_cbranch_vccnz .LBB0_835
	global_store_dwordx4 v[44:45], v[16:19], off
	s_cbranch_execnz .LBB0_584

.LBB0_593:
	s_and_b64 vcc, exec, s[4:5]
	s_cbranch_vccnz .LBB0_595
	v_mul_f32_e32 v40, v17, v17
	v_mul_f32_e32 v41, v19, v19
	v_fmac_f32_e32 v40, v16, v16
	v_fmac_f32_e32 v41, v18, v18
	v_add_f32_e32 v40, v40, v41
	v_mul_f32_e32 v41, v21, v21
	v_mul_f32_e32 v42, v23, v23
	v_fmac_f32_e32 v41, v20, v20
	v_fmac_f32_e32 v42, v22, v22
	v_add_f32_e32 v41, v41, v42
	v_add_f32_e32 v40, v40, v41
	v_mul_f32_e32 v41, v25, v25
	v_mul_f32_e32 v42, v27, v27
	v_fmac_f32_e32 v41, v24, v24
	v_fmac_f32_e32 v42, v26, v26
	v_add_f32_e32 v41, v41, v42
	v_add_f32_e32 v40, v41, v40
	v_mul_f32_e32 v41, v29, v29
	v_mul_f32_e32 v42, v31, v31
	v_fmac_f32_e32 v41, v28, v28
	v_fmac_f32_e32 v42, v30, v30
	v_add_f32_e32 v41, v41, v42
	v_add_f32_e32 v40, v41, v40
	s_nop 1
	v_mov_b32_dpp v41, v40 quad_perm:[1,0,3,2] row_mask:0xf bank_mask:0xf
	s_waitcnt lgkmcnt(0)
	v_add_f32_e32 v40, v40, v41
	s_nop 1
	v_mov_b32_dpp v41, v40 quad_perm:[2,3,0,1] row_mask:0xf bank_mask:0xf
	s_waitcnt lgkmcnt(0)
	v_add_f32_e32 v40, v40, v41
	s_nop 1
	v_mov_b32_dpp v41, v40 row_half_mirror row_mask:0xf bank_mask:0xf
	s_waitcnt lgkmcnt(0)
	v_add_f32_e32 v40, v40, v41
	s_nop 1
	v_mov_b32_dpp v41, v40 row_mirror row_mask:0xf bank_mask:0xf
	s_waitcnt lgkmcnt(0)
	v_add_f32_e32 v40, v40, v41
	ds_bpermute_b32 v41, v252, v40
	s_waitcnt lgkmcnt(0)
	v_add_f32_e32 v40, v40, v41
	ds_bpermute_b32 v41, v246, v40
	s_waitcnt lgkmcnt(0)
	v_add_f32_e32 v40, v40, v41
	v_fmamk_f32 v40, v40, 0x3a800000, v247
	v_mul_f32_e32 v41, 0x4b800000, v40
	v_cmp_gt_f32_e32 vcc, s35, v40
	s_nop 1
	v_cndmask_b32_e32 v40, v40, v41, vcc
	v_rsq_f32_e32 v42, v40
	v_lshl_add_u64 v[40:41], v[196:197], 1, s[42:43]
	v_mul_f32_e32 v43, 0x45800000, v42
	v_cndmask_b32_e32 v42, v42, v43, vcc
	v_pk_mul_f32 v[16:17], v[16:17], v[42:43] op_sel_hi:[1,0]
	v_pk_mul_f32 v[18:19], v[18:19], v[42:43] op_sel_hi:[1,0]
	v_pk_mul_f32 v[20:21], v[20:21], v[42:43] op_sel_hi:[1,0]
	v_pk_mul_f32 v[22:23], v[22:23], v[42:43] op_sel_hi:[1,0]
	v_pk_fma_f32 v[18:19], v[54:55], v[18:19], v[2:3]
	v_pk_fma_f32 v[16:17], v[52:53], v[16:17], v[0:1]
	v_pk_fma_f32 v[22:23], v[56:57], v[22:23], v[6:7]
	v_pk_fma_f32 v[20:21], v[50:51], v[20:21], v[4:5]
	v_cvt_pk_bf16_f32 v16, v16, v17
	v_cvt_pk_bf16_f32 v17, v18, v19
	v_cvt_pk_bf16_f32 v18, v20, v21
	v_cvt_pk_bf16_f32 v19, v22, v23
	global_store_dwordx2 v[40:41], v[16:17], off
	global_store_dwordx2 v[40:41], v[18:19], off offset:512
	v_pk_mul_f32 v[16:17], v[24:25], v[42:43] op_sel_hi:[1,0]
	v_pk_mul_f32 v[18:19], v[26:27], v[42:43] op_sel_hi:[1,0]
	v_pk_fma_f32 v[16:17], v[60:61], v[16:17], v[8:9]
	v_pk_fma_f32 v[18:19], v[62:63], v[18:19], v[10:11]
	v_cvt_pk_bf16_f32 v16, v16, v17
	v_cvt_pk_bf16_f32 v17, v18, v19
	global_store_dwordx2 v[40:41], v[16:17], off offset:1024
	v_pk_mul_f32 v[16:17], v[28:29], v[42:43] op_sel_hi:[1,0]
	v_pk_mul_f32 v[18:19], v[30:31], v[42:43] op_sel_hi:[1,0]
	v_pk_fma_f32 v[16:17], v[58:59], v[16:17], v[12:13]
	v_pk_fma_f32 v[18:19], v[64:65], v[18:19], v[14:15]
	v_cvt_pk_bf16_f32 v16, v16, v17
	v_cvt_pk_bf16_f32 v17, v18, v19
	global_store_dwordx2 v[40:41], v[16:17], off offset:1536
.LBB0_595:
	v_and_b32_e32 v17, 0xffff0000, v194
	v_and_b32_e32 v19, 0xffff0000, v195
	v_lshlrev_b32_e32 v16, 16, v194
	v_lshlrev_b32_e32 v18, 16, v195
	v_mul_f32_e32 v20, v19, v19
	v_and_b32_e32 v23, 0xffff0000, v193
	v_and_b32_e32 v22, 0xffff0000, v192
	v_and_b32_e32 v29, 0xffff0000, v188
	v_mul_f32_e32 v28, v17, v17
	v_pk_fma_f32 v[42:43], v[18:19], v[18:19], v[20:21] op_sel_hi:[1,1,0]
	v_lshlrev_b32_e32 v21, 16, v193
	v_lshlrev_b32_e32 v20, 16, v192
	v_pk_mul_f32 v[24:25], v[22:23], v[22:23]
	v_lshlrev_b32_e32 v31, 16, v188
	v_pk_fma_f32 v[46:47], v[16:17], v[16:17], v[28:29] op_sel_hi:[1,1,0]
	v_pk_fma_f32 v[44:45], v[20:21], v[20:21], v[24:25]
	v_mov_b32_e32 v30, v46
	v_mov_b32_e32 v48, v42
	v_mov_b32_e32 v49, v31
	v_and_b32_e32 v25, 0xffff0000, v190
	v_mul_f32_e32 v188, v29, v29
	v_pk_add_f32 v[42:43], v[46:47], v[42:43]
	v_pk_mul_f32 v[46:47], v[30:31], v[48:49]
	v_pk_add_f32 v[44:45], v[44:45], v[44:45] op_sel:[0,1] op_sel_hi:[1,0]
	v_lshlrev_b32_e32 v24, 16, v190
	v_and_b32_e32 v27, 0xffff0000, v191
	v_mov_b32_e32 v43, v47
	v_mov_b32_e32 v45, v188
	v_mul_f32_e32 v28, v25, v25
	v_lshlrev_b32_e32 v26, 16, v191
	v_lshlrev_b32_e32 v40, 16, v189
	v_and_b32_e32 v41, 0xffff0000, v189
	v_pk_add_f32 v[42:43], v[42:43], v[44:45]
	v_pk_fma_f32 v[44:45], v[24:25], v[24:25], v[28:29] op_sel_hi:[1,1,0]
	v_mul_f32_e32 v28, v27, v27
	v_mul_f32_e32 v189, v40, v40
	v_mul_f32_e32 v190, v41, v41
	v_pk_fma_f32 v[46:47], v[26:27], v[26:27], v[28:29] op_sel_hi:[1,1,0]
	v_mov_b32_e32 v45, v189
	v_mov_b32_e32 v47, v190
	v_pk_add_f32 v[44:45], v[44:45], v[46:47]
	v_lshlrev_b32_e32 v46, 16, v187
	v_pk_add_f32 v[42:43], v[42:43], v[44:45]
	v_lshlrev_b32_e32 v44, 16, v186
	v_add_f32_e32 v28, v42, v43
	s_nop 1
	v_mov_b32_dpp v30, v28 quad_perm:[1,0,3,2] row_mask:0xf bank_mask:0xf
	v_and_b32_e32 v45, 0xffff0000, v186
	v_and_b32_e32 v47, 0xffff0000, v187
	s_waitcnt lgkmcnt(0)
	v_add_f32_e32 v28, v28, v30
	s_nop 1
	v_mov_b32_dpp v30, v28 quad_perm:[2,3,0,1] row_mask:0xf bank_mask:0xf
	s_waitcnt lgkmcnt(0)
	v_add_f32_e32 v28, v28, v30
	s_nop 1
	v_mov_b32_dpp v30, v28 row_half_mirror row_mask:0xf bank_mask:0xf
	s_waitcnt lgkmcnt(0)
	v_add_f32_e32 v28, v28, v30
	s_nop 1
	v_mov_b32_dpp v30, v28 row_mirror row_mask:0xf bank_mask:0xf
	s_waitcnt lgkmcnt(0)
	v_add_f32_e32 v28, v28, v30
	ds_bpermute_b32 v30, v252, v28
	s_waitcnt lgkmcnt(0)
	v_add_f32_e32 v28, v28, v30
	ds_bpermute_b32 v30, v246, v28
	s_waitcnt lgkmcnt(0)
	v_add_f32_e32 v28, v28, v30
	v_fmamk_f32 v28, v28, 0x3a800000, v247
	v_mul_f32_e32 v30, 0x4b800000, v28
	v_cmp_gt_f32_e32 vcc, s35, v28
	s_nop 1
	v_cndmask_b32_e32 v28, v28, v30, vcc
	v_rsq_f32_e32 v28, v28
	s_nop 0
	v_mul_f32_e32 v30, 0x45800000, v28
	v_cndmask_b32_e32 v42, v28, v30, vcc
	v_pk_mul_f32 v[16:17], v[42:43], v[16:17] op_sel_hi:[0,1]
	v_pk_mul_f32 v[18:19], v[42:43], v[18:19] op_sel_hi:[0,1]
	v_pk_fma_f32 v[18:19], v[88:89], v[18:19], v[46:47]
	v_pk_fma_f32 v[16:17], v[86:87], v[16:17], v[44:45]
	s_and_b64 vcc, exec, s[6:7]
	v_lshl_add_u64 v[44:45], v[176:177], 2, s[0:1]
	s_cbranch_vccnz .LBB0_839
	global_store_dwordx4 v[44:45], v[16:19], off
	s_cbranch_execnz .LBB0_598

.LBB0_607:
	s_and_b64 vcc, exec, s[4:5]
	s_cbranch_vccnz .LBB0_609
	v_mul_f32_e32 v40, v17, v17
	v_mul_f32_e32 v41, v19, v19
	v_fmac_f32_e32 v40, v16, v16
	v_fmac_f32_e32 v41, v18, v18
	v_add_f32_e32 v40, v40, v41
	v_mul_f32_e32 v41, v21, v21
	v_mul_f32_e32 v42, v23, v23
	v_fmac_f32_e32 v41, v20, v20
	v_fmac_f32_e32 v42, v22, v22
	v_add_f32_e32 v41, v41, v42
	v_add_f32_e32 v40, v40, v41
	v_mul_f32_e32 v41, v25, v25
	v_mul_f32_e32 v42, v27, v27
	v_fmac_f32_e32 v41, v24, v24
	v_fmac_f32_e32 v42, v26, v26
	v_add_f32_e32 v41, v41, v42
	v_add_f32_e32 v40, v41, v40
	v_mul_f32_e32 v41, v29, v29
	v_mul_f32_e32 v42, v31, v31
	v_fmac_f32_e32 v41, v28, v28
	v_fmac_f32_e32 v42, v30, v30
	v_add_f32_e32 v41, v41, v42
	v_add_f32_e32 v40, v41, v40
	s_nop 1
	v_mov_b32_dpp v41, v40 quad_perm:[1,0,3,2] row_mask:0xf bank_mask:0xf
	s_waitcnt lgkmcnt(0)
	v_add_f32_e32 v40, v40, v41
	s_nop 1
	v_mov_b32_dpp v41, v40 quad_perm:[2,3,0,1] row_mask:0xf bank_mask:0xf
	s_waitcnt lgkmcnt(0)
	v_add_f32_e32 v40, v40, v41
	s_nop 1
	v_mov_b32_dpp v41, v40 row_half_mirror row_mask:0xf bank_mask:0xf
	s_waitcnt lgkmcnt(0)
	v_add_f32_e32 v40, v40, v41
	s_nop 1
	v_mov_b32_dpp v41, v40 row_mirror row_mask:0xf bank_mask:0xf
	s_waitcnt lgkmcnt(0)
	v_add_f32_e32 v40, v40, v41
	ds_bpermute_b32 v41, v252, v40
	s_waitcnt lgkmcnt(0)
	v_add_f32_e32 v40, v40, v41
	ds_bpermute_b32 v41, v246, v40
	s_waitcnt lgkmcnt(0)
	v_add_f32_e32 v40, v40, v41
	v_fmamk_f32 v40, v40, 0x3a800000, v247
	v_mul_f32_e32 v41, 0x4b800000, v40
	v_cmp_gt_f32_e32 vcc, s35, v40
	s_nop 1
	v_cndmask_b32_e32 v40, v40, v41, vcc
	v_rsq_f32_e32 v42, v40
	v_lshl_add_u64 v[40:41], v[176:177], 1, s[42:43]
	v_mul_f32_e32 v43, 0x45800000, v42
	v_cndmask_b32_e32 v42, v42, v43, vcc
	v_pk_mul_f32 v[16:17], v[16:17], v[42:43] op_sel_hi:[1,0]
	v_pk_mul_f32 v[18:19], v[18:19], v[42:43] op_sel_hi:[1,0]
	v_pk_mul_f32 v[20:21], v[20:21], v[42:43] op_sel_hi:[1,0]
	v_pk_mul_f32 v[22:23], v[22:23], v[42:43] op_sel_hi:[1,0]
	v_pk_fma_f32 v[18:19], v[54:55], v[18:19], v[2:3]
	v_pk_fma_f32 v[16:17], v[52:53], v[16:17], v[0:1]
	v_pk_fma_f32 v[22:23], v[56:57], v[22:23], v[6:7]
	v_pk_fma_f32 v[20:21], v[50:51], v[20:21], v[4:5]
	v_cvt_pk_bf16_f32 v16, v16, v17
	v_cvt_pk_bf16_f32 v17, v18, v19
	v_cvt_pk_bf16_f32 v18, v20, v21
	v_cvt_pk_bf16_f32 v19, v22, v23
	global_store_dwordx2 v[40:41], v[16:17], off
	global_store_dwordx2 v[40:41], v[18:19], off offset:512
	v_pk_mul_f32 v[16:17], v[24:25], v[42:43] op_sel_hi:[1,0]
	v_pk_mul_f32 v[18:19], v[26:27], v[42:43] op_sel_hi:[1,0]
	v_pk_fma_f32 v[16:17], v[60:61], v[16:17], v[8:9]
	v_pk_fma_f32 v[18:19], v[62:63], v[18:19], v[10:11]
	v_cvt_pk_bf16_f32 v16, v16, v17
	v_cvt_pk_bf16_f32 v17, v18, v19
	global_store_dwordx2 v[40:41], v[16:17], off offset:1024
	v_pk_mul_f32 v[16:17], v[28:29], v[42:43] op_sel_hi:[1,0]
	v_pk_mul_f32 v[18:19], v[30:31], v[42:43] op_sel_hi:[1,0]
	v_pk_fma_f32 v[16:17], v[58:59], v[16:17], v[12:13]
	v_pk_fma_f32 v[18:19], v[64:65], v[18:19], v[14:15]
	v_cvt_pk_bf16_f32 v16, v16, v17
	v_cvt_pk_bf16_f32 v17, v18, v19
	global_store_dwordx2 v[40:41], v[16:17], off offset:1536
.LBB0_609:
	v_and_b32_e32 v17, 0xffff0000, v174
	v_and_b32_e32 v19, 0xffff0000, v175
	v_lshlrev_b32_e32 v16, 16, v174
	v_lshlrev_b32_e32 v18, 16, v175
	v_mul_f32_e32 v20, v19, v19
	v_and_b32_e32 v23, 0xffff0000, v173
	v_and_b32_e32 v22, 0xffff0000, v172
	v_and_b32_e32 v29, 0xffff0000, v168
	v_mul_f32_e32 v28, v17, v17
	v_pk_fma_f32 v[42:43], v[18:19], v[18:19], v[20:21] op_sel_hi:[1,1,0]
	v_lshlrev_b32_e32 v21, 16, v173
	v_lshlrev_b32_e32 v20, 16, v172
	v_pk_mul_f32 v[24:25], v[22:23], v[22:23]
	v_lshlrev_b32_e32 v31, 16, v168
	v_pk_fma_f32 v[46:47], v[16:17], v[16:17], v[28:29] op_sel_hi:[1,1,0]
	v_pk_fma_f32 v[44:45], v[20:21], v[20:21], v[24:25]
	v_mov_b32_e32 v30, v46
	v_mov_b32_e32 v48, v42
	v_mov_b32_e32 v49, v31
	v_and_b32_e32 v25, 0xffff0000, v170
	v_mul_f32_e32 v168, v29, v29
	v_pk_add_f32 v[42:43], v[46:47], v[42:43]
	v_pk_mul_f32 v[46:47], v[30:31], v[48:49]
	v_pk_add_f32 v[44:45], v[44:45], v[44:45] op_sel:[0,1] op_sel_hi:[1,0]
	v_lshlrev_b32_e32 v24, 16, v170
	v_and_b32_e32 v27, 0xffff0000, v171
	v_mov_b32_e32 v43, v47
	v_mov_b32_e32 v45, v168
	v_mul_f32_e32 v28, v25, v25
	v_lshlrev_b32_e32 v26, 16, v171
	v_lshlrev_b32_e32 v40, 16, v169
	v_and_b32_e32 v41, 0xffff0000, v169
	v_pk_add_f32 v[42:43], v[42:43], v[44:45]
	v_pk_fma_f32 v[44:45], v[24:25], v[24:25], v[28:29] op_sel_hi:[1,1,0]
	v_mul_f32_e32 v28, v27, v27
	v_mul_f32_e32 v169, v40, v40
	v_mul_f32_e32 v170, v41, v41
	v_pk_fma_f32 v[46:47], v[26:27], v[26:27], v[28:29] op_sel_hi:[1,1,0]
	v_mov_b32_e32 v45, v169
	v_mov_b32_e32 v47, v170
	v_pk_add_f32 v[44:45], v[44:45], v[46:47]
	v_lshlrev_b32_e32 v46, 16, v167
	v_pk_add_f32 v[42:43], v[42:43], v[44:45]
	v_lshlrev_b32_e32 v44, 16, v166
	v_add_f32_e32 v28, v42, v43
	s_nop 1
	v_mov_b32_dpp v30, v28 quad_perm:[1,0,3,2] row_mask:0xf bank_mask:0xf
	v_and_b32_e32 v45, 0xffff0000, v166
	v_and_b32_e32 v47, 0xffff0000, v167
	s_waitcnt lgkmcnt(0)
	v_add_f32_e32 v28, v28, v30
	s_nop 1
	v_mov_b32_dpp v30, v28 quad_perm:[2,3,0,1] row_mask:0xf bank_mask:0xf
	s_waitcnt lgkmcnt(0)
	v_add_f32_e32 v28, v28, v30
	s_nop 1
	v_mov_b32_dpp v30, v28 row_half_mirror row_mask:0xf bank_mask:0xf
	s_waitcnt lgkmcnt(0)
	v_add_f32_e32 v28, v28, v30
	s_nop 1
	v_mov_b32_dpp v30, v28 row_mirror row_mask:0xf bank_mask:0xf
	s_waitcnt lgkmcnt(0)
	v_add_f32_e32 v28, v28, v30
	ds_bpermute_b32 v30, v252, v28
	s_waitcnt lgkmcnt(0)
	v_add_f32_e32 v28, v28, v30
	ds_bpermute_b32 v30, v246, v28
	s_waitcnt lgkmcnt(0)
	v_add_f32_e32 v28, v28, v30
	v_fmamk_f32 v28, v28, 0x3a800000, v247
	v_mul_f32_e32 v30, 0x4b800000, v28
	v_cmp_gt_f32_e32 vcc, s35, v28
	s_nop 1
	v_cndmask_b32_e32 v28, v28, v30, vcc
	v_rsq_f32_e32 v28, v28
	s_nop 0
	v_mul_f32_e32 v30, 0x45800000, v28
	v_cndmask_b32_e32 v42, v28, v30, vcc
	v_pk_mul_f32 v[16:17], v[42:43], v[16:17] op_sel_hi:[0,1]
	v_pk_mul_f32 v[18:19], v[42:43], v[18:19] op_sel_hi:[0,1]
	v_pk_fma_f32 v[18:19], v[88:89], v[18:19], v[46:47]
	v_pk_fma_f32 v[16:17], v[86:87], v[16:17], v[44:45]
	s_and_b64 vcc, exec, s[6:7]
	v_lshl_add_u64 v[44:45], v[156:157], 2, s[0:1]
	s_cbranch_vccnz .LBB0_843
	global_store_dwordx4 v[44:45], v[16:19], off
	s_cbranch_execnz .LBB0_612

.LBB0_621:
	s_and_b64 vcc, exec, s[4:5]
	s_cbranch_vccnz .LBB0_623
	v_mul_f32_e32 v40, v17, v17
	v_mul_f32_e32 v41, v19, v19
	v_fmac_f32_e32 v40, v16, v16
	v_fmac_f32_e32 v41, v18, v18
	v_add_f32_e32 v40, v40, v41
	v_mul_f32_e32 v41, v21, v21
	v_mul_f32_e32 v42, v23, v23
	v_fmac_f32_e32 v41, v20, v20
	v_fmac_f32_e32 v42, v22, v22
	v_add_f32_e32 v41, v41, v42
	v_add_f32_e32 v40, v40, v41
	v_mul_f32_e32 v41, v25, v25
	v_mul_f32_e32 v42, v27, v27
	v_fmac_f32_e32 v41, v24, v24
	v_fmac_f32_e32 v42, v26, v26
	v_add_f32_e32 v41, v41, v42
	v_add_f32_e32 v40, v41, v40
	v_mul_f32_e32 v41, v29, v29
	v_mul_f32_e32 v42, v31, v31
	v_fmac_f32_e32 v41, v28, v28
	v_fmac_f32_e32 v42, v30, v30
	v_add_f32_e32 v41, v41, v42
	v_add_f32_e32 v40, v41, v40
	s_nop 1
	v_mov_b32_dpp v41, v40 quad_perm:[1,0,3,2] row_mask:0xf bank_mask:0xf
	s_waitcnt lgkmcnt(0)
	v_add_f32_e32 v40, v40, v41
	s_nop 1
	v_mov_b32_dpp v41, v40 quad_perm:[2,3,0,1] row_mask:0xf bank_mask:0xf
	s_waitcnt lgkmcnt(0)
	v_add_f32_e32 v40, v40, v41
	s_nop 1
	v_mov_b32_dpp v41, v40 row_half_mirror row_mask:0xf bank_mask:0xf
	s_waitcnt lgkmcnt(0)
	v_add_f32_e32 v40, v40, v41
	s_nop 1
	v_mov_b32_dpp v41, v40 row_mirror row_mask:0xf bank_mask:0xf
	s_waitcnt lgkmcnt(0)
	v_add_f32_e32 v40, v40, v41
	ds_bpermute_b32 v41, v252, v40
	s_waitcnt lgkmcnt(0)
	v_add_f32_e32 v40, v40, v41
	ds_bpermute_b32 v41, v246, v40
	s_waitcnt lgkmcnt(0)
	v_add_f32_e32 v40, v40, v41
	v_fmamk_f32 v40, v40, 0x3a800000, v247
	v_mul_f32_e32 v41, 0x4b800000, v40
	v_cmp_gt_f32_e32 vcc, s35, v40
	s_nop 1
	v_cndmask_b32_e32 v40, v40, v41, vcc
	v_rsq_f32_e32 v42, v40
	v_lshl_add_u64 v[40:41], v[156:157], 1, s[42:43]
	v_mul_f32_e32 v43, 0x45800000, v42
	v_cndmask_b32_e32 v42, v42, v43, vcc
	v_pk_mul_f32 v[16:17], v[16:17], v[42:43] op_sel_hi:[1,0]
	v_pk_mul_f32 v[18:19], v[18:19], v[42:43] op_sel_hi:[1,0]
	v_pk_mul_f32 v[20:21], v[20:21], v[42:43] op_sel_hi:[1,0]
	v_pk_mul_f32 v[22:23], v[22:23], v[42:43] op_sel_hi:[1,0]
	v_pk_fma_f32 v[18:19], v[54:55], v[18:19], v[2:3]
	v_pk_fma_f32 v[16:17], v[52:53], v[16:17], v[0:1]
	v_pk_fma_f32 v[22:23], v[56:57], v[22:23], v[6:7]
	v_pk_fma_f32 v[20:21], v[50:51], v[20:21], v[4:5]
	v_cvt_pk_bf16_f32 v16, v16, v17
	v_cvt_pk_bf16_f32 v17, v18, v19
	v_cvt_pk_bf16_f32 v18, v20, v21
	v_cvt_pk_bf16_f32 v19, v22, v23
	global_store_dwordx2 v[40:41], v[16:17], off
	global_store_dwordx2 v[40:41], v[18:19], off offset:512
	v_pk_mul_f32 v[16:17], v[24:25], v[42:43] op_sel_hi:[1,0]
	v_pk_mul_f32 v[18:19], v[26:27], v[42:43] op_sel_hi:[1,0]
	v_pk_fma_f32 v[16:17], v[60:61], v[16:17], v[8:9]
	v_pk_fma_f32 v[18:19], v[62:63], v[18:19], v[10:11]
	v_cvt_pk_bf16_f32 v16, v16, v17
	v_cvt_pk_bf16_f32 v17, v18, v19
	global_store_dwordx2 v[40:41], v[16:17], off offset:1024
	v_pk_mul_f32 v[16:17], v[28:29], v[42:43] op_sel_hi:[1,0]
	v_pk_mul_f32 v[18:19], v[30:31], v[42:43] op_sel_hi:[1,0]
	v_pk_fma_f32 v[16:17], v[58:59], v[16:17], v[12:13]
	v_pk_fma_f32 v[18:19], v[64:65], v[18:19], v[14:15]
	v_cvt_pk_bf16_f32 v16, v16, v17
	v_cvt_pk_bf16_f32 v17, v18, v19
	global_store_dwordx2 v[40:41], v[16:17], off offset:1536
.LBB0_623:
	v_and_b32_e32 v17, 0xffff0000, v154
	v_and_b32_e32 v19, 0xffff0000, v155
	v_lshlrev_b32_e32 v16, 16, v154
	v_lshlrev_b32_e32 v18, 16, v155
	v_mul_f32_e32 v20, v19, v19
	v_and_b32_e32 v23, 0xffff0000, v153
	v_and_b32_e32 v22, 0xffff0000, v152
	v_and_b32_e32 v29, 0xffff0000, v148
	v_mul_f32_e32 v28, v17, v17
	v_pk_fma_f32 v[42:43], v[18:19], v[18:19], v[20:21] op_sel_hi:[1,1,0]
	v_lshlrev_b32_e32 v21, 16, v153
	v_lshlrev_b32_e32 v20, 16, v152
	v_pk_mul_f32 v[24:25], v[22:23], v[22:23]
	v_lshlrev_b32_e32 v31, 16, v148
	v_pk_fma_f32 v[46:47], v[16:17], v[16:17], v[28:29] op_sel_hi:[1,1,0]
	v_pk_fma_f32 v[44:45], v[20:21], v[20:21], v[24:25]
	v_mov_b32_e32 v30, v46
	v_mov_b32_e32 v48, v42
	v_mov_b32_e32 v49, v31
	v_and_b32_e32 v25, 0xffff0000, v150
	v_mul_f32_e32 v148, v29, v29
	v_pk_add_f32 v[42:43], v[46:47], v[42:43]
	v_pk_mul_f32 v[46:47], v[30:31], v[48:49]
	v_pk_add_f32 v[44:45], v[44:45], v[44:45] op_sel:[0,1] op_sel_hi:[1,0]
	v_lshlrev_b32_e32 v24, 16, v150
	v_and_b32_e32 v27, 0xffff0000, v151
	v_mov_b32_e32 v43, v47
	v_mov_b32_e32 v45, v148
	v_mul_f32_e32 v28, v25, v25
	v_lshlrev_b32_e32 v26, 16, v151
	v_lshlrev_b32_e32 v40, 16, v149
	v_and_b32_e32 v41, 0xffff0000, v149
	v_pk_add_f32 v[42:43], v[42:43], v[44:45]
	v_pk_fma_f32 v[44:45], v[24:25], v[24:25], v[28:29] op_sel_hi:[1,1,0]
	v_mul_f32_e32 v28, v27, v27
	v_mul_f32_e32 v149, v40, v40
	v_mul_f32_e32 v150, v41, v41
	v_pk_fma_f32 v[46:47], v[26:27], v[26:27], v[28:29] op_sel_hi:[1,1,0]
	v_mov_b32_e32 v45, v149
	v_mov_b32_e32 v47, v150
	v_pk_add_f32 v[44:45], v[44:45], v[46:47]
	v_lshlrev_b32_e32 v46, 16, v147
	v_pk_add_f32 v[42:43], v[42:43], v[44:45]
	v_lshlrev_b32_e32 v44, 16, v146
	v_add_f32_e32 v28, v42, v43
	s_nop 1
	v_mov_b32_dpp v30, v28 quad_perm:[1,0,3,2] row_mask:0xf bank_mask:0xf
	v_and_b32_e32 v45, 0xffff0000, v146
	v_and_b32_e32 v47, 0xffff0000, v147
	s_waitcnt lgkmcnt(0)
	v_add_f32_e32 v28, v28, v30
	s_nop 1
	v_mov_b32_dpp v30, v28 quad_perm:[2,3,0,1] row_mask:0xf bank_mask:0xf
	s_waitcnt lgkmcnt(0)
	v_add_f32_e32 v28, v28, v30
	s_nop 1
	v_mov_b32_dpp v30, v28 row_half_mirror row_mask:0xf bank_mask:0xf
	s_waitcnt lgkmcnt(0)
	v_add_f32_e32 v28, v28, v30
	s_nop 1
	v_mov_b32_dpp v30, v28 row_mirror row_mask:0xf bank_mask:0xf
	s_waitcnt lgkmcnt(0)
	v_add_f32_e32 v28, v28, v30
	ds_bpermute_b32 v30, v252, v28
	s_waitcnt lgkmcnt(0)
	v_add_f32_e32 v28, v28, v30
	ds_bpermute_b32 v30, v246, v28
	s_waitcnt lgkmcnt(0)
	v_add_f32_e32 v28, v28, v30
	v_fmamk_f32 v28, v28, 0x3a800000, v247
	v_mul_f32_e32 v30, 0x4b800000, v28
	v_cmp_gt_f32_e32 vcc, s35, v28
	s_nop 1
	v_cndmask_b32_e32 v28, v28, v30, vcc
	v_rsq_f32_e32 v28, v28
	s_nop 0
	v_mul_f32_e32 v30, 0x45800000, v28
	v_cndmask_b32_e32 v42, v28, v30, vcc
	v_pk_mul_f32 v[16:17], v[42:43], v[16:17] op_sel_hi:[0,1]
	v_pk_mul_f32 v[18:19], v[42:43], v[18:19] op_sel_hi:[0,1]
	v_pk_fma_f32 v[18:19], v[88:89], v[18:19], v[46:47]
	v_pk_fma_f32 v[16:17], v[86:87], v[16:17], v[44:45]
	s_and_b64 vcc, exec, s[6:7]
	v_lshl_add_u64 v[44:45], v[134:135], 2, s[0:1]
	s_cbranch_vccnz .LBB0_847
	global_store_dwordx4 v[44:45], v[16:19], off
	s_cbranch_execnz .LBB0_626

.LBB0_635:
	s_and_b64 vcc, exec, s[4:5]
	s_cbranch_vccnz .LBB0_637
	v_mul_f32_e32 v40, v17, v17
	v_mul_f32_e32 v41, v19, v19
	v_fmac_f32_e32 v40, v16, v16
	v_fmac_f32_e32 v41, v18, v18
	v_add_f32_e32 v40, v40, v41
	v_mul_f32_e32 v41, v21, v21
	v_mul_f32_e32 v42, v23, v23
	v_fmac_f32_e32 v41, v20, v20
	v_fmac_f32_e32 v42, v22, v22
	v_add_f32_e32 v41, v41, v42
	v_add_f32_e32 v40, v40, v41
	v_mul_f32_e32 v41, v25, v25
	v_mul_f32_e32 v42, v27, v27
	v_fmac_f32_e32 v41, v24, v24
	v_fmac_f32_e32 v42, v26, v26
	v_add_f32_e32 v41, v41, v42
	v_add_f32_e32 v40, v41, v40
	v_mul_f32_e32 v41, v29, v29
	v_mul_f32_e32 v42, v31, v31
	v_fmac_f32_e32 v41, v28, v28
	v_fmac_f32_e32 v42, v30, v30
	v_add_f32_e32 v41, v41, v42
	v_add_f32_e32 v40, v41, v40
	s_nop 1
	v_mov_b32_dpp v41, v40 quad_perm:[1,0,3,2] row_mask:0xf bank_mask:0xf
	s_waitcnt lgkmcnt(0)
	v_add_f32_e32 v40, v40, v41
	s_nop 1
	v_mov_b32_dpp v41, v40 quad_perm:[2,3,0,1] row_mask:0xf bank_mask:0xf
	s_waitcnt lgkmcnt(0)
	v_add_f32_e32 v40, v40, v41
	s_nop 1
	v_mov_b32_dpp v41, v40 row_half_mirror row_mask:0xf bank_mask:0xf
	s_waitcnt lgkmcnt(0)
	v_add_f32_e32 v40, v40, v41
	s_nop 1
	v_mov_b32_dpp v41, v40 row_mirror row_mask:0xf bank_mask:0xf
	s_waitcnt lgkmcnt(0)
	v_add_f32_e32 v40, v40, v41
	ds_bpermute_b32 v41, v252, v40
	s_waitcnt lgkmcnt(0)
	v_add_f32_e32 v40, v40, v41
	ds_bpermute_b32 v41, v246, v40
	s_waitcnt lgkmcnt(0)
	v_add_f32_e32 v40, v40, v41
	v_fmamk_f32 v40, v40, 0x3a800000, v247
	v_mul_f32_e32 v41, 0x4b800000, v40
	v_cmp_gt_f32_e32 vcc, s35, v40
	s_nop 1
	v_cndmask_b32_e32 v40, v40, v41, vcc
	v_rsq_f32_e32 v42, v40
	v_lshl_add_u64 v[40:41], v[134:135], 1, s[42:43]
	v_mul_f32_e32 v43, 0x45800000, v42
	v_cndmask_b32_e32 v42, v42, v43, vcc
	v_pk_mul_f32 v[16:17], v[16:17], v[42:43] op_sel_hi:[1,0]
	v_pk_mul_f32 v[18:19], v[18:19], v[42:43] op_sel_hi:[1,0]
	v_pk_mul_f32 v[20:21], v[20:21], v[42:43] op_sel_hi:[1,0]
	v_pk_mul_f32 v[22:23], v[22:23], v[42:43] op_sel_hi:[1,0]
	v_pk_fma_f32 v[18:19], v[54:55], v[18:19], v[2:3]
	v_pk_fma_f32 v[16:17], v[52:53], v[16:17], v[0:1]
	v_pk_fma_f32 v[22:23], v[56:57], v[22:23], v[6:7]
	v_pk_fma_f32 v[20:21], v[50:51], v[20:21], v[4:5]
	v_cvt_pk_bf16_f32 v16, v16, v17
	v_cvt_pk_bf16_f32 v17, v18, v19
	v_cvt_pk_bf16_f32 v18, v20, v21
	v_cvt_pk_bf16_f32 v19, v22, v23
	global_store_dwordx2 v[40:41], v[16:17], off
	global_store_dwordx2 v[40:41], v[18:19], off offset:512
	v_pk_mul_f32 v[16:17], v[24:25], v[42:43] op_sel_hi:[1,0]
	v_pk_mul_f32 v[18:19], v[26:27], v[42:43] op_sel_hi:[1,0]
	v_pk_fma_f32 v[16:17], v[60:61], v[16:17], v[8:9]
	v_pk_fma_f32 v[18:19], v[62:63], v[18:19], v[10:11]
	v_cvt_pk_bf16_f32 v16, v16, v17
	v_cvt_pk_bf16_f32 v17, v18, v19
	global_store_dwordx2 v[40:41], v[16:17], off offset:1024
	v_pk_mul_f32 v[16:17], v[28:29], v[42:43] op_sel_hi:[1,0]
	v_pk_mul_f32 v[18:19], v[30:31], v[42:43] op_sel_hi:[1,0]
	v_pk_fma_f32 v[16:17], v[58:59], v[16:17], v[12:13]
	v_pk_fma_f32 v[18:19], v[64:65], v[18:19], v[14:15]
	v_cvt_pk_bf16_f32 v16, v16, v17
	v_cvt_pk_bf16_f32 v17, v18, v19
	global_store_dwordx2 v[40:41], v[16:17], off offset:1536
.LBB0_637:
	v_and_b32_e32 v17, 0xffff0000, v132
	v_and_b32_e32 v19, 0xffff0000, v133
	v_lshlrev_b32_e32 v16, 16, v132
	v_lshlrev_b32_e32 v18, 16, v133
	v_mul_f32_e32 v20, v19, v19
	v_and_b32_e32 v23, 0xffff0000, v131
	v_and_b32_e32 v22, 0xffff0000, v130
	v_and_b32_e32 v29, 0xffff0000, v126
	v_mul_f32_e32 v28, v17, v17
	v_pk_fma_f32 v[42:43], v[18:19], v[18:19], v[20:21] op_sel_hi:[1,1,0]
	v_lshlrev_b32_e32 v21, 16, v131
	v_lshlrev_b32_e32 v20, 16, v130
	v_pk_mul_f32 v[24:25], v[22:23], v[22:23]
	v_lshlrev_b32_e32 v31, 16, v126
	v_pk_fma_f32 v[46:47], v[16:17], v[16:17], v[28:29] op_sel_hi:[1,1,0]
	v_pk_fma_f32 v[44:45], v[20:21], v[20:21], v[24:25]
	v_mov_b32_e32 v30, v46
	v_mov_b32_e32 v48, v42
	v_mov_b32_e32 v49, v31
	v_and_b32_e32 v25, 0xffff0000, v128
	v_mul_f32_e32 v126, v29, v29
	v_pk_add_f32 v[42:43], v[46:47], v[42:43]
	v_pk_mul_f32 v[46:47], v[30:31], v[48:49]
	v_pk_add_f32 v[44:45], v[44:45], v[44:45] op_sel:[0,1] op_sel_hi:[1,0]
	v_lshlrev_b32_e32 v24, 16, v128
	v_and_b32_e32 v27, 0xffff0000, v129
	v_mov_b32_e32 v43, v47
	v_mov_b32_e32 v45, v126
	v_mul_f32_e32 v28, v25, v25
	v_lshlrev_b32_e32 v26, 16, v129
	v_lshlrev_b32_e32 v40, 16, v127
	v_and_b32_e32 v41, 0xffff0000, v127
	v_pk_add_f32 v[42:43], v[42:43], v[44:45]
	v_pk_fma_f32 v[44:45], v[24:25], v[24:25], v[28:29] op_sel_hi:[1,1,0]
	v_mul_f32_e32 v28, v27, v27
	v_mul_f32_e32 v127, v40, v40
	v_mul_f32_e32 v128, v41, v41
	v_pk_fma_f32 v[46:47], v[26:27], v[26:27], v[28:29] op_sel_hi:[1,1,0]
	v_mov_b32_e32 v45, v127
	v_mov_b32_e32 v47, v128
	v_pk_add_f32 v[44:45], v[44:45], v[46:47]
	v_lshlrev_b32_e32 v46, 16, v125
	v_pk_add_f32 v[42:43], v[42:43], v[44:45]
	v_lshlrev_b32_e32 v44, 16, v124
	v_add_f32_e32 v28, v42, v43
	s_nop 1
	v_mov_b32_dpp v30, v28 quad_perm:[1,0,3,2] row_mask:0xf bank_mask:0xf
	v_and_b32_e32 v45, 0xffff0000, v124
	v_and_b32_e32 v47, 0xffff0000, v125
	s_waitcnt lgkmcnt(0)
	v_add_f32_e32 v28, v28, v30
	s_nop 1
	v_mov_b32_dpp v30, v28 quad_perm:[2,3,0,1] row_mask:0xf bank_mask:0xf
	s_waitcnt lgkmcnt(0)
	v_add_f32_e32 v28, v28, v30
	s_nop 1
	v_mov_b32_dpp v30, v28 row_half_mirror row_mask:0xf bank_mask:0xf
	s_waitcnt lgkmcnt(0)
	v_add_f32_e32 v28, v28, v30
	s_nop 1
	v_mov_b32_dpp v30, v28 row_mirror row_mask:0xf bank_mask:0xf
	s_waitcnt lgkmcnt(0)
	v_add_f32_e32 v28, v28, v30
	ds_bpermute_b32 v30, v252, v28
	s_waitcnt lgkmcnt(0)
	v_add_f32_e32 v28, v28, v30
	ds_bpermute_b32 v30, v246, v28
	s_waitcnt lgkmcnt(0)
	v_add_f32_e32 v28, v28, v30
	v_fmamk_f32 v28, v28, 0x3a800000, v247
	v_mul_f32_e32 v30, 0x4b800000, v28
	v_cmp_gt_f32_e32 vcc, s35, v28
	s_nop 1
	v_cndmask_b32_e32 v28, v28, v30, vcc
	v_rsq_f32_e32 v28, v28
	s_nop 0
	v_mul_f32_e32 v30, 0x45800000, v28
	v_cndmask_b32_e32 v42, v28, v30, vcc
	v_pk_mul_f32 v[16:17], v[42:43], v[16:17] op_sel_hi:[0,1]
	v_pk_mul_f32 v[18:19], v[42:43], v[18:19] op_sel_hi:[0,1]
	v_pk_fma_f32 v[18:19], v[88:89], v[18:19], v[46:47]
	v_pk_fma_f32 v[16:17], v[86:87], v[16:17], v[44:45]
	s_and_b64 vcc, exec, s[6:7]
	v_lshl_add_u64 v[44:45], v[114:115], 2, s[0:1]
	s_cbranch_vccnz .LBB0_851
	global_store_dwordx4 v[44:45], v[16:19], off
	s_cbranch_execnz .LBB0_640

.LBB0_649:
	s_and_b64 vcc, exec, s[4:5]
	s_cbranch_vccnz .LBB0_651
	v_mul_f32_e32 v40, v17, v17
	v_mul_f32_e32 v41, v19, v19
	v_fmac_f32_e32 v40, v16, v16
	v_fmac_f32_e32 v41, v18, v18
	v_add_f32_e32 v40, v40, v41
	v_mul_f32_e32 v41, v21, v21
	v_mul_f32_e32 v42, v23, v23
	v_fmac_f32_e32 v41, v20, v20
	v_fmac_f32_e32 v42, v22, v22
	v_add_f32_e32 v41, v41, v42
	v_add_f32_e32 v40, v40, v41
	v_mul_f32_e32 v41, v25, v25
	v_mul_f32_e32 v42, v27, v27
	v_fmac_f32_e32 v41, v24, v24
	v_fmac_f32_e32 v42, v26, v26
	v_add_f32_e32 v41, v41, v42
	v_add_f32_e32 v40, v41, v40
	v_mul_f32_e32 v41, v29, v29
	v_mul_f32_e32 v42, v31, v31
	v_fmac_f32_e32 v41, v28, v28
	v_fmac_f32_e32 v42, v30, v30
	v_add_f32_e32 v41, v41, v42
	v_add_f32_e32 v40, v41, v40
	s_nop 1
	v_mov_b32_dpp v41, v40 quad_perm:[1,0,3,2] row_mask:0xf bank_mask:0xf
	s_waitcnt lgkmcnt(0)
	v_add_f32_e32 v40, v40, v41
	s_nop 1
	v_mov_b32_dpp v41, v40 quad_perm:[2,3,0,1] row_mask:0xf bank_mask:0xf
	s_waitcnt lgkmcnt(0)
	v_add_f32_e32 v40, v40, v41
	s_nop 1
	v_mov_b32_dpp v41, v40 row_half_mirror row_mask:0xf bank_mask:0xf
	s_waitcnt lgkmcnt(0)
	v_add_f32_e32 v40, v40, v41
	s_nop 1
	v_mov_b32_dpp v41, v40 row_mirror row_mask:0xf bank_mask:0xf
	s_waitcnt lgkmcnt(0)
	v_add_f32_e32 v40, v40, v41
	ds_bpermute_b32 v41, v252, v40
	s_waitcnt lgkmcnt(0)
	v_add_f32_e32 v40, v40, v41
	ds_bpermute_b32 v41, v246, v40
	s_waitcnt lgkmcnt(0)
	v_add_f32_e32 v40, v40, v41
	v_fmamk_f32 v40, v40, 0x3a800000, v247
	v_mul_f32_e32 v41, 0x4b800000, v40
	v_cmp_gt_f32_e32 vcc, s35, v40
	s_nop 1
	v_cndmask_b32_e32 v40, v40, v41, vcc
	v_rsq_f32_e32 v42, v40
	v_lshl_add_u64 v[40:41], v[114:115], 1, s[42:43]
	v_mul_f32_e32 v43, 0x45800000, v42
	v_cndmask_b32_e32 v42, v42, v43, vcc
	v_pk_mul_f32 v[16:17], v[16:17], v[42:43] op_sel_hi:[1,0]
	v_pk_mul_f32 v[18:19], v[18:19], v[42:43] op_sel_hi:[1,0]
	v_pk_mul_f32 v[20:21], v[20:21], v[42:43] op_sel_hi:[1,0]
	v_pk_mul_f32 v[22:23], v[22:23], v[42:43] op_sel_hi:[1,0]
	v_pk_fma_f32 v[18:19], v[54:55], v[18:19], v[2:3]
	v_pk_fma_f32 v[16:17], v[52:53], v[16:17], v[0:1]
	v_pk_fma_f32 v[22:23], v[56:57], v[22:23], v[6:7]
	v_pk_fma_f32 v[20:21], v[50:51], v[20:21], v[4:5]
	v_cvt_pk_bf16_f32 v16, v16, v17
	v_cvt_pk_bf16_f32 v17, v18, v19
	v_cvt_pk_bf16_f32 v18, v20, v21
	v_cvt_pk_bf16_f32 v19, v22, v23
	global_store_dwordx2 v[40:41], v[16:17], off
	global_store_dwordx2 v[40:41], v[18:19], off offset:512
	v_pk_mul_f32 v[16:17], v[24:25], v[42:43] op_sel_hi:[1,0]
	v_pk_mul_f32 v[18:19], v[26:27], v[42:43] op_sel_hi:[1,0]
	v_pk_fma_f32 v[16:17], v[60:61], v[16:17], v[8:9]
	v_pk_fma_f32 v[18:19], v[62:63], v[18:19], v[10:11]
	v_cvt_pk_bf16_f32 v16, v16, v17
	v_cvt_pk_bf16_f32 v17, v18, v19
	global_store_dwordx2 v[40:41], v[16:17], off offset:1024
	v_pk_mul_f32 v[16:17], v[28:29], v[42:43] op_sel_hi:[1,0]
	v_pk_mul_f32 v[18:19], v[30:31], v[42:43] op_sel_hi:[1,0]
	v_pk_fma_f32 v[16:17], v[58:59], v[16:17], v[12:13]
	v_pk_fma_f32 v[18:19], v[64:65], v[18:19], v[14:15]
	v_cvt_pk_bf16_f32 v16, v16, v17
	v_cvt_pk_bf16_f32 v17, v18, v19
	global_store_dwordx2 v[40:41], v[16:17], off offset:1536
.LBB0_651:
	v_and_b32_e32 v17, 0xffff0000, v112
	v_and_b32_e32 v19, 0xffff0000, v113
	v_lshlrev_b32_e32 v16, 16, v112
	v_lshlrev_b32_e32 v18, 16, v113
	v_mul_f32_e32 v20, v19, v19
	v_and_b32_e32 v23, 0xffff0000, v111
	v_and_b32_e32 v22, 0xffff0000, v110
	v_and_b32_e32 v29, 0xffff0000, v106
	v_mul_f32_e32 v28, v17, v17
	v_pk_fma_f32 v[42:43], v[18:19], v[18:19], v[20:21] op_sel_hi:[1,1,0]
	v_lshlrev_b32_e32 v21, 16, v111
	v_lshlrev_b32_e32 v20, 16, v110
	v_pk_mul_f32 v[24:25], v[22:23], v[22:23]
	v_lshlrev_b32_e32 v31, 16, v106
	v_pk_fma_f32 v[46:47], v[16:17], v[16:17], v[28:29] op_sel_hi:[1,1,0]
	v_pk_fma_f32 v[44:45], v[20:21], v[20:21], v[24:25]
	v_mov_b32_e32 v30, v46
	v_mov_b32_e32 v48, v42
	v_mov_b32_e32 v49, v31
	v_and_b32_e32 v25, 0xffff0000, v108
	v_mul_f32_e32 v106, v29, v29
	v_pk_add_f32 v[42:43], v[46:47], v[42:43]
	v_pk_mul_f32 v[46:47], v[30:31], v[48:49]
	v_pk_add_f32 v[44:45], v[44:45], v[44:45] op_sel:[0,1] op_sel_hi:[1,0]
	v_lshlrev_b32_e32 v24, 16, v108
	v_and_b32_e32 v27, 0xffff0000, v109
	v_mov_b32_e32 v43, v47
	v_mov_b32_e32 v45, v106
	v_mul_f32_e32 v28, v25, v25
	v_lshlrev_b32_e32 v26, 16, v109
	v_lshlrev_b32_e32 v40, 16, v107
	v_and_b32_e32 v41, 0xffff0000, v107
	v_pk_add_f32 v[42:43], v[42:43], v[44:45]
	v_pk_fma_f32 v[44:45], v[24:25], v[24:25], v[28:29] op_sel_hi:[1,1,0]
	v_mul_f32_e32 v28, v27, v27
	v_mul_f32_e32 v107, v40, v40
	v_mul_f32_e32 v108, v41, v41
	v_pk_fma_f32 v[46:47], v[26:27], v[26:27], v[28:29] op_sel_hi:[1,1,0]
	v_mov_b32_e32 v45, v107
	v_mov_b32_e32 v47, v108
	v_pk_add_f32 v[44:45], v[44:45], v[46:47]
	v_lshlrev_b32_e32 v46, 16, v105
	v_pk_add_f32 v[42:43], v[42:43], v[44:45]
	v_lshlrev_b32_e32 v44, 16, v104
	v_add_f32_e32 v28, v42, v43
	s_nop 1
	v_mov_b32_dpp v30, v28 quad_perm:[1,0,3,2] row_mask:0xf bank_mask:0xf
	v_and_b32_e32 v45, 0xffff0000, v104
	v_and_b32_e32 v47, 0xffff0000, v105
	s_waitcnt lgkmcnt(0)
	v_add_f32_e32 v28, v28, v30
	s_nop 1
	v_mov_b32_dpp v30, v28 quad_perm:[2,3,0,1] row_mask:0xf bank_mask:0xf
	s_waitcnt lgkmcnt(0)
	v_add_f32_e32 v28, v28, v30
	s_nop 1
	v_mov_b32_dpp v30, v28 row_half_mirror row_mask:0xf bank_mask:0xf
	s_waitcnt lgkmcnt(0)
	v_add_f32_e32 v28, v28, v30
	s_nop 1
	v_mov_b32_dpp v30, v28 row_mirror row_mask:0xf bank_mask:0xf
	s_waitcnt lgkmcnt(0)
	v_add_f32_e32 v28, v28, v30
	ds_bpermute_b32 v30, v252, v28
	s_waitcnt lgkmcnt(0)
	v_add_f32_e32 v28, v28, v30
	ds_bpermute_b32 v30, v246, v28
	s_waitcnt lgkmcnt(0)
	v_add_f32_e32 v28, v28, v30
	v_fmamk_f32 v28, v28, 0x3a800000, v247
	v_mul_f32_e32 v30, 0x4b800000, v28
	v_cmp_gt_f32_e32 vcc, s35, v28
	s_nop 1
	v_cndmask_b32_e32 v28, v28, v30, vcc
	v_rsq_f32_e32 v28, v28
	s_nop 0
	v_mul_f32_e32 v30, 0x45800000, v28
	v_cndmask_b32_e32 v42, v28, v30, vcc
	v_pk_mul_f32 v[16:17], v[42:43], v[16:17] op_sel_hi:[0,1]
	v_pk_mul_f32 v[18:19], v[42:43], v[18:19] op_sel_hi:[0,1]
	v_pk_fma_f32 v[18:19], v[88:89], v[18:19], v[46:47]
	v_pk_fma_f32 v[16:17], v[86:87], v[16:17], v[44:45]
	s_and_b64 vcc, exec, s[6:7]
	v_lshl_add_u64 v[44:45], v[94:95], 2, s[0:1]
	s_cbranch_vccnz .LBB0_855
	global_store_dwordx4 v[44:45], v[16:19], off
	s_cbranch_execnz .LBB0_654

.LBB0_663:
	s_and_b64 vcc, exec, s[4:5]
	s_cbranch_vccnz .LBB0_665
	v_mul_f32_e32 v40, v17, v17
	v_mul_f32_e32 v41, v19, v19
	v_fmac_f32_e32 v40, v16, v16
	v_fmac_f32_e32 v41, v18, v18
	v_add_f32_e32 v40, v40, v41
	v_mul_f32_e32 v41, v21, v21
	v_mul_f32_e32 v42, v23, v23
	v_fmac_f32_e32 v41, v20, v20
	v_fmac_f32_e32 v42, v22, v22
	v_add_f32_e32 v41, v41, v42
	v_add_f32_e32 v40, v40, v41
	v_mul_f32_e32 v41, v25, v25
	v_mul_f32_e32 v42, v27, v27
	v_fmac_f32_e32 v41, v24, v24
	v_fmac_f32_e32 v42, v26, v26
	v_add_f32_e32 v41, v41, v42
	v_add_f32_e32 v40, v41, v40
	v_mul_f32_e32 v41, v29, v29
	v_mul_f32_e32 v42, v31, v31
	v_fmac_f32_e32 v41, v28, v28
	v_fmac_f32_e32 v42, v30, v30
	v_add_f32_e32 v41, v41, v42
	v_add_f32_e32 v40, v41, v40
	s_nop 1
	v_mov_b32_dpp v41, v40 quad_perm:[1,0,3,2] row_mask:0xf bank_mask:0xf
	s_waitcnt lgkmcnt(0)
	v_add_f32_e32 v40, v40, v41
	s_nop 1
	v_mov_b32_dpp v41, v40 quad_perm:[2,3,0,1] row_mask:0xf bank_mask:0xf
	s_waitcnt lgkmcnt(0)
	v_add_f32_e32 v40, v40, v41
	s_nop 1
	v_mov_b32_dpp v41, v40 row_half_mirror row_mask:0xf bank_mask:0xf
	s_waitcnt lgkmcnt(0)
	v_add_f32_e32 v40, v40, v41
	s_nop 1
	v_mov_b32_dpp v41, v40 row_mirror row_mask:0xf bank_mask:0xf
	s_waitcnt lgkmcnt(0)
	v_add_f32_e32 v40, v40, v41
	ds_bpermute_b32 v41, v252, v40
	s_waitcnt lgkmcnt(0)
	v_add_f32_e32 v40, v40, v41
	ds_bpermute_b32 v41, v246, v40
	s_waitcnt lgkmcnt(0)
	v_add_f32_e32 v40, v40, v41
	v_fmamk_f32 v40, v40, 0x3a800000, v247
	v_mul_f32_e32 v41, 0x4b800000, v40
	v_cmp_gt_f32_e32 vcc, s35, v40
	s_nop 1
	v_cndmask_b32_e32 v40, v40, v41, vcc
	v_rsq_f32_e32 v42, v40
	v_lshl_add_u64 v[40:41], v[94:95], 1, s[42:43]
	v_mul_f32_e32 v43, 0x45800000, v42
	v_cndmask_b32_e32 v42, v42, v43, vcc
	v_pk_mul_f32 v[16:17], v[16:17], v[42:43] op_sel_hi:[1,0]
	v_pk_mul_f32 v[18:19], v[18:19], v[42:43] op_sel_hi:[1,0]
	v_pk_mul_f32 v[20:21], v[20:21], v[42:43] op_sel_hi:[1,0]
	v_pk_mul_f32 v[22:23], v[22:23], v[42:43] op_sel_hi:[1,0]
	v_pk_fma_f32 v[18:19], v[54:55], v[18:19], v[2:3]
	v_pk_fma_f32 v[16:17], v[52:53], v[16:17], v[0:1]
	v_pk_fma_f32 v[22:23], v[56:57], v[22:23], v[6:7]
	v_pk_fma_f32 v[20:21], v[50:51], v[20:21], v[4:5]
	v_cvt_pk_bf16_f32 v16, v16, v17
	v_cvt_pk_bf16_f32 v17, v18, v19
	v_cvt_pk_bf16_f32 v18, v20, v21
	v_cvt_pk_bf16_f32 v19, v22, v23
	global_store_dwordx2 v[40:41], v[16:17], off
	global_store_dwordx2 v[40:41], v[18:19], off offset:512
	v_pk_mul_f32 v[16:17], v[24:25], v[42:43] op_sel_hi:[1,0]
	v_pk_mul_f32 v[18:19], v[26:27], v[42:43] op_sel_hi:[1,0]
	v_pk_fma_f32 v[16:17], v[60:61], v[16:17], v[8:9]
	v_pk_fma_f32 v[18:19], v[62:63], v[18:19], v[10:11]
	v_cvt_pk_bf16_f32 v16, v16, v17
	v_cvt_pk_bf16_f32 v17, v18, v19
	global_store_dwordx2 v[40:41], v[16:17], off offset:1024
	v_pk_mul_f32 v[16:17], v[28:29], v[42:43] op_sel_hi:[1,0]
	v_pk_mul_f32 v[18:19], v[30:31], v[42:43] op_sel_hi:[1,0]
	v_pk_fma_f32 v[16:17], v[58:59], v[16:17], v[12:13]
	v_pk_fma_f32 v[18:19], v[64:65], v[18:19], v[14:15]
	v_cvt_pk_bf16_f32 v16, v16, v17
	v_cvt_pk_bf16_f32 v17, v18, v19
	global_store_dwordx2 v[40:41], v[16:17], off offset:1536
.LBB0_665:
	v_and_b32_e32 v17, 0xffff0000, v84
	v_and_b32_e32 v19, 0xffff0000, v85
	v_lshlrev_b32_e32 v16, 16, v84
	v_lshlrev_b32_e32 v18, 16, v85
	v_mul_f32_e32 v20, v19, v19
	v_and_b32_e32 v23, 0xffff0000, v83
	v_and_b32_e32 v22, 0xffff0000, v82
	v_and_b32_e32 v29, 0xffff0000, v78
	v_mul_f32_e32 v28, v17, v17
	v_pk_fma_f32 v[42:43], v[18:19], v[18:19], v[20:21] op_sel_hi:[1,1,0]
	v_lshlrev_b32_e32 v21, 16, v83
	v_lshlrev_b32_e32 v20, 16, v82
	v_pk_mul_f32 v[24:25], v[22:23], v[22:23]
	v_lshlrev_b32_e32 v31, 16, v78
	v_pk_fma_f32 v[46:47], v[16:17], v[16:17], v[28:29] op_sel_hi:[1,1,0]
	v_pk_fma_f32 v[44:45], v[20:21], v[20:21], v[24:25]
	v_mov_b32_e32 v30, v46
	v_mov_b32_e32 v48, v42
	v_mov_b32_e32 v49, v31
	v_and_b32_e32 v25, 0xffff0000, v80
	v_mul_f32_e32 v78, v29, v29
	v_pk_add_f32 v[42:43], v[46:47], v[42:43]
	v_pk_mul_f32 v[46:47], v[30:31], v[48:49]
	v_pk_add_f32 v[44:45], v[44:45], v[44:45] op_sel:[0,1] op_sel_hi:[1,0]
	v_lshlrev_b32_e32 v24, 16, v80
	v_and_b32_e32 v27, 0xffff0000, v81
	v_mov_b32_e32 v43, v47
	v_mov_b32_e32 v45, v78
	v_mul_f32_e32 v28, v25, v25
	v_lshlrev_b32_e32 v26, 16, v81
	v_lshlrev_b32_e32 v40, 16, v79
	v_and_b32_e32 v41, 0xffff0000, v79
	v_pk_add_f32 v[42:43], v[42:43], v[44:45]
	v_pk_fma_f32 v[44:45], v[24:25], v[24:25], v[28:29] op_sel_hi:[1,1,0]
	v_mul_f32_e32 v28, v27, v27
	v_mul_f32_e32 v79, v40, v40
	v_mul_f32_e32 v80, v41, v41
	v_pk_fma_f32 v[46:47], v[26:27], v[26:27], v[28:29] op_sel_hi:[1,1,0]
	v_mov_b32_e32 v45, v79
	v_mov_b32_e32 v47, v80
	v_pk_add_f32 v[44:45], v[44:45], v[46:47]
	v_lshlrev_b32_e32 v46, 16, v77
	v_pk_add_f32 v[42:43], v[42:43], v[44:45]
	v_lshlrev_b32_e32 v44, 16, v76
	v_add_f32_e32 v28, v42, v43
	s_nop 1
	v_mov_b32_dpp v30, v28 quad_perm:[1,0,3,2] row_mask:0xf bank_mask:0xf
	v_and_b32_e32 v45, 0xffff0000, v76
	v_and_b32_e32 v47, 0xffff0000, v77
	s_waitcnt lgkmcnt(0)
	v_add_f32_e32 v28, v28, v30
	s_nop 1
	v_mov_b32_dpp v30, v28 quad_perm:[2,3,0,1] row_mask:0xf bank_mask:0xf
	s_waitcnt lgkmcnt(0)
	v_add_f32_e32 v28, v28, v30
	s_nop 1
	v_mov_b32_dpp v30, v28 row_half_mirror row_mask:0xf bank_mask:0xf
	s_waitcnt lgkmcnt(0)
	v_add_f32_e32 v28, v28, v30
	s_nop 1
	v_mov_b32_dpp v30, v28 row_mirror row_mask:0xf bank_mask:0xf
	s_waitcnt lgkmcnt(0)
	v_add_f32_e32 v28, v28, v30
	ds_bpermute_b32 v30, v252, v28
	s_waitcnt lgkmcnt(0)
	v_add_f32_e32 v28, v28, v30
	ds_bpermute_b32 v30, v246, v28
	s_waitcnt lgkmcnt(0)
	v_add_f32_e32 v28, v28, v30
	v_fmamk_f32 v28, v28, 0x3a800000, v247
	v_mul_f32_e32 v30, 0x4b800000, v28
	v_cmp_gt_f32_e32 vcc, s35, v28
	s_nop 1
	v_cndmask_b32_e32 v28, v28, v30, vcc
	v_rsq_f32_e32 v28, v28
	s_nop 0
	v_mul_f32_e32 v30, 0x45800000, v28
	v_cndmask_b32_e32 v42, v28, v30, vcc
	v_pk_mul_f32 v[16:17], v[42:43], v[16:17] op_sel_hi:[0,1]
	v_pk_mul_f32 v[18:19], v[42:43], v[18:19] op_sel_hi:[0,1]
	v_pk_fma_f32 v[18:19], v[88:89], v[18:19], v[46:47]
	v_pk_fma_f32 v[16:17], v[86:87], v[16:17], v[44:45]
	s_and_b64 vcc, exec, s[6:7]
	v_lshl_add_u64 v[44:45], v[66:67], 2, s[0:1]
	s_cbranch_vccnz .LBB0_859
	global_store_dwordx4 v[44:45], v[16:19], off
	s_cbranch_execnz .LBB0_668

.LBB0_677:
	s_and_b64 vcc, exec, s[4:5]
	s_cbranch_vccnz .LBB0_679
	v_mul_f32_e32 v32, v17, v17
	v_mul_f32_e32 v33, v19, v19
	v_fmac_f32_e32 v32, v16, v16
	v_fmac_f32_e32 v33, v18, v18
	v_add_f32_e32 v32, v32, v33
	v_mul_f32_e32 v33, v21, v21
	v_mul_f32_e32 v34, v23, v23
	v_fmac_f32_e32 v33, v20, v20
	v_fmac_f32_e32 v34, v22, v22
	v_add_f32_e32 v33, v33, v34
	v_add_f32_e32 v32, v32, v33
	v_mul_f32_e32 v33, v25, v25
	v_mul_f32_e32 v34, v27, v27
	v_fmac_f32_e32 v33, v24, v24
	v_fmac_f32_e32 v34, v26, v26
	v_add_f32_e32 v33, v33, v34
	v_add_f32_e32 v32, v33, v32
	v_mul_f32_e32 v33, v29, v29
	v_mul_f32_e32 v34, v31, v31
	v_fmac_f32_e32 v33, v28, v28
	v_fmac_f32_e32 v34, v30, v30
	v_add_f32_e32 v33, v33, v34
	v_add_f32_e32 v32, v33, v32
	s_nop 1
	v_mov_b32_dpp v33, v32 quad_perm:[1,0,3,2] row_mask:0xf bank_mask:0xf
	s_mov_b64 s[4:5], 0
	s_waitcnt lgkmcnt(0)
	v_add_f32_e32 v32, v32, v33
	s_nop 1
	v_mov_b32_dpp v33, v32 quad_perm:[2,3,0,1] row_mask:0xf bank_mask:0xf
	s_waitcnt lgkmcnt(0)
	v_add_f32_e32 v32, v32, v33
	s_nop 1
	v_mov_b32_dpp v33, v32 row_half_mirror row_mask:0xf bank_mask:0xf
	s_waitcnt lgkmcnt(0)
	v_add_f32_e32 v32, v32, v33
	s_nop 1
	v_mov_b32_dpp v33, v32 row_mirror row_mask:0xf bank_mask:0xf
	s_waitcnt lgkmcnt(0)
	v_add_f32_e32 v32, v32, v33
	ds_bpermute_b32 v33, v252, v32
	s_waitcnt lgkmcnt(0)
	v_add_f32_e32 v32, v32, v33
	ds_bpermute_b32 v33, v246, v32
	s_waitcnt lgkmcnt(0)
	v_add_f32_e32 v32, v32, v33
	v_fmamk_f32 v32, v32, 0x3a800000, v247
	v_mul_f32_e32 v33, 0x4b800000, v32
	v_cmp_gt_f32_e32 vcc, s35, v32
	s_nop 1
	v_cndmask_b32_e32 v32, v32, v33, vcc
	v_rsq_f32_e32 v34, v32
	v_lshl_add_u64 v[32:33], v[66:67], 1, s[42:43]
	v_mul_f32_e32 v35, 0x45800000, v34
	v_cndmask_b32_e32 v34, v34, v35, vcc
	v_pk_mul_f32 v[16:17], v[16:17], v[34:35] op_sel_hi:[1,0]
	v_pk_mul_f32 v[18:19], v[18:19], v[34:35] op_sel_hi:[1,0]
	v_pk_mul_f32 v[20:21], v[20:21], v[34:35] op_sel_hi:[1,0]
	v_pk_mul_f32 v[22:23], v[22:23], v[34:35] op_sel_hi:[1,0]
	v_pk_fma_f32 v[2:3], v[54:55], v[18:19], v[2:3]
	v_pk_fma_f32 v[0:1], v[52:53], v[16:17], v[0:1]
	v_pk_fma_f32 v[6:7], v[56:57], v[22:23], v[6:7]
	v_pk_fma_f32 v[4:5], v[50:51], v[20:21], v[4:5]
	v_cvt_pk_bf16_f32 v0, v0, v1
	v_cvt_pk_bf16_f32 v1, v2, v3
	v_cvt_pk_bf16_f32 v2, v4, v5
	v_cvt_pk_bf16_f32 v3, v6, v7
	global_store_dwordx2 v[32:33], v[0:1], off
	global_store_dwordx2 v[32:33], v[2:3], off offset:512
	v_pk_mul_f32 v[0:1], v[24:25], v[34:35] op_sel_hi:[1,0]
	v_pk_mul_f32 v[2:3], v[26:27], v[34:35] op_sel_hi:[1,0]
	v_pk_fma_f32 v[0:1], v[60:61], v[0:1], v[8:9]
	v_pk_fma_f32 v[2:3], v[62:63], v[2:3], v[10:11]
	v_cvt_pk_bf16_f32 v0, v0, v1
	v_cvt_pk_bf16_f32 v1, v2, v3
	global_store_dwordx2 v[32:33], v[0:1], off offset:1024
	v_pk_mul_f32 v[0:1], v[28:29], v[34:35] op_sel_hi:[1,0]
	v_pk_mul_f32 v[2:3], v[30:31], v[34:35] op_sel_hi:[1,0]
	v_pk_fma_f32 v[0:1], v[58:59], v[0:1], v[12:13]
	v_pk_fma_f32 v[2:3], v[64:65], v[2:3], v[14:15]
	v_cvt_pk_bf16_f32 v0, v0, v1
	v_cvt_pk_bf16_f32 v1, v2, v3
	global_store_dwordx2 v[32:33], v[0:1], off offset:1536
	s_branch .LBB0_680
